# c6 + grid barrier: everyone polls the cross-XCD arrival counter (TOP) directly, dropping the TOPGEN and XGEN hops
# baseline (speedup 1.0000x reference)
.LBB0_53:
	s_lshl_b32 s98, s33, 8
	s_add_u32 s98, s24, s98
	s_addc_u32 s99, s25, 0
	v_mov_b32_e32 v3, 0x1000
	v_mov_b32_e32 v4, 1
	global_atomic_add v3, v3, v4, s[98:99] offset:1024 sc0
	v_cvt_f32_u32_e32 v4, v2
	v_sub_u32_e32 v5, 0, v2
	v_mov_b32_e32 v7, 0x3000
	v_rcp_iflag_f32_e32 v4, v4
	v_mov_b32_e32 v10, 0
	v_mul_f32_e32 v4, 0x4f7ffffe, v4
	v_cvt_u32_f32_e32 v4, v4
	v_mul_lo_u32 v5, v5, v4
	v_mul_hi_u32 v5, v4, v5
	v_add_u32_e32 v4, v4, v5
	s_waitcnt vmcnt(0) lgkmcnt(0)
	v_mul_hi_u32 v1, v3, v4
	v_mul_lo_u32 v5, v1, v2
	v_sub_u32_e32 v5, v3, v5
	v_add_u32_e32 v6, 1, v1
	v_cmp_ge_u32_e32 vcc, v5, v2
	v_sub_u32_e32 v8, v5, v2
	s_nop 1
	v_cndmask_b32_e32 v1, v1, v6, vcc
	v_cndmask_b32_e32 v5, v5, v8, vcc
	v_add_u32_e32 v6, 1, v1
	v_cmp_ge_u32_e32 vcc, v5, v2
	v_sub_u32_e32 v8, v5, v2
	s_nop 1
	v_cndmask_b32_e32 v1, v1, v6, vcc
	v_cndmask_b32_e32 v5, v5, v8, vcc
	v_add_u32_e32 v5, 1, v5
	v_mad_u32_u24 v6, v1, v0, v0
	v_cmp_eq_u32_e32 vcc, v5, v2
	s_and_saveexec_b64 s[100:101], vcc
	s_cbranch_execz .Lxb0_nl
	buffer_wbl2 sc1
	s_waitcnt vmcnt(0)
	v_mov_b32_e32 v8, 1
	global_atomic_add v7, v8, s[24:25] offset:1024
.Lxb0_nl:
	s_or_b64 exec, exec, s[100:101]
	s_mov_b32 s98, 0
.Lxb0_poll:
	global_load_dword v8, v7, s[24:25] offset:1024 sc1
	s_add_i32 s98, s98, 1
	s_waitcnt vmcnt(0)
	v_cmp_ge_u32_e32 vcc, v8, v6
	s_cbranch_vccnz .Lxb0_done
	s_sleep 1
	s_and_b32 s99, s98, 0xff
	s_cmp_lg_u32 s99, 0
	s_cbranch_scc1 .Lxb0_poll
	global_load_dword v9, v10, s[24:25] offset:512 sc1
	s_waitcnt vmcnt(0)
	v_cmp_ne_u32_e32 vcc, 0, v9
	s_cbranch_vccnz .Lxb0_done
	s_cmp_lt_u32 s98, 0x40001
	s_cbranch_scc1 .Lxb0_poll
	v_mov_b32_e32 v9, 1
	global_atomic_add v10, v9, s[24:25] offset:512
.Lxb0_done:
	s_waitcnt vmcnt(0)
	buffer_inv sc1
	s_waitcnt vmcnt(0)
